# v35 + GEMM tile prologue: k-tile-1 LDS-DMA loads issued before the first wait (vmcnt(10)), six compiler false-WAW vmcnt drains in tile setup removed
# baseline (speedup 1.0000x reference)
; __device__ __forceinline__ void phase_gemm(const Params& p, int kind, int j, unsigned char* lds) {
;     ...
;         } else if (kind == 5) {
;             tile_order(L, T / BM, 8, pm, pn);
;             td.A = rkvz + (size_t)3 * T * D; td.Bt = wtb + WT_R_OUT / 2; td.ep.mode = 0; td.ep.out = big + B_OUTF_R;
.LBB0_222:
	s_cmp_gt_i32 s54, 4
	s_cbranch_scc0 .LBB0_227
	s_cmp_eq_u32 s54, 5
	s_mov_b64 s[12:13], -1
	s_cbranch_scc0 .LBB0_225
	s_ashr_i32 s2, s60, 31
	s_lshr_b32 s2, s2, 29
	s_add_i32 s2, s60, s2
	s_ashr_i32 s3, s2, 3
	s_and_b32 s2, s2, -8
	s_sub_i32 s2, s60, s2
	s_cmp_lt_i32 s2, 0
	s_movk_i32 s4, 0x61
	s_cselect_b32 s4, s4, 0x60
	s_mul_i32 s2, s4, s2
	s_add_i32 s2, s2, s3
	s_ashr_i32 s3, s2, 31
	s_lshr_b32 s3, s3, 26
	s_add_i32 s3, s2, s3
	s_ashr_i32 s4, s3, 6
	s_lshl_b32 s4, s4, 3
	s_sub_i32 s5, 0x60, s4
	s_min_i32 s5, s5, 8
	v_cvt_f32_i32_e32 v0, s5
	s_andn2_b32 s3, s3, 63
	s_sub_i32 s6, s2, s3
	v_cvt_f32_i32_e32 v1, s6
	v_rcp_iflag_f32_e32 v2, v0
	s_xor_b32 s2, s6, s5
	s_ashr_i32 s2, s2, 30
	s_or_b32 s7, s2, 1
	v_mul_f32_e32 v2, v1, v2
	v_trunc_f32_e32 v2, v2
	v_fma_f32 v1, -v2, v0, v1
	v_cvt_i32_f32_e32 v2, v2
	v_cmp_ge_f32_e64 s[2:3], |v1|, |v0|
	s_and_b64 s[2:3], s[2:3], exec
	s_cselect_b32 s2, s7, 0
	v_readfirstlane_b32 s3, v2
	s_add_i32 s2, s3, s2
	s_sext_i32_i16 s64, s2
	s_mul_i32 s2, s2, s5
	s_sub_i32 s2, s6, s2
	s_sext_i32_i16 s2, s2
	s_add_i32 s2, s4, s2
	s_mov_b64 s[12:13], 0

; __device__ __forceinline__ void phase_gemm(const Params& p, int kind, int j, unsigned char* lds) {
;     ...
;             } else {
;                 tile_order(L - main_tiles, nM, 5, pm, pn);
;                 const int xsel = (pn < 2) ? 1 : (pn < 4) ? 4 : 3;
;                 td.A = xs + (size_t)xsel * T * D; td.Bt = wtb + WT_R_L1 / 2;
;                 td.ep.mode = (pn < 2) ? 1 : 0; td.ep.ldo = 1280; td.ep.out = big + B_LORA;
;             }
.LBB0_227:
	s_cbranch_execz .LBB0_226
	s_cmp_eq_u32 s54, 3
	s_mov_b64 s[12:13], -1
	s_cbranch_scc0 .LBB0_234
	s_cmpk_gt_i32 s60, 0xbff
	s_mov_b64 s[6:7], -1
	s_cbranch_scc0 .LBB0_231
	s_add_i32 s2, s60, 0xfffff400
	s_and_b32 s3, s60, 7
	s_mul_i32 s3, s3, 60
	s_lshr_b32 s2, s2, 3
	s_add_i32 s3, s3, s2
	s_mul_hi_u32 s2, s3, 0xcccccccd
	s_lshr_b32 s2, s2, 5
	s_lshl_b32 s4, s2, 3
	s_sub_i32 s5, 0x60, s4
	s_min_u32 s5, s5, 8
	s_mul_i32 s2, s2, 40
	s_sub_i32 s6, s3, s2
	v_cvt_f32_ubyte0_e32 v1, s5
	v_cvt_f32_u32_e32 v0, s6
	v_rcp_iflag_f32_e32 v2, v1
	s_nop 0
	v_mul_f32_e32 v2, v0, v2
	v_trunc_f32_e32 v2, v2
	v_fma_f32 v0, -v2, v1, v0
	v_cvt_u32_f32_e32 v2, v2
	v_cmp_ge_f32_e64 s[2:3], |v0|, v1
	s_cmp_lg_u64 s[2:3], 0
	s_mov_b32 s3, 0x9000000
	v_readfirstlane_b32 s7, v2
	s_addc_u32 s2, s7, 0
	s_and_b32 s64, s2, 0xff
	s_mul_i32 s2, s2, s5
	s_sub_i32 s2, s6, s2
	s_and_b32 s2, s2, 0xff
	s_add_i32 s2, s4, s2
	s_cmp_lt_u32 s64, 4
	s_cselect_b32 s3, 0xc000000, s3
	s_cmp_lt_u32 s64, 2
	s_cselect_b64 s[6:7], -1, 0
	s_and_b64 s[4:5], s[6:7], exec
	s_cselect_b32 s3, 0x3000000, s3
	s_lshl_b32 s3, s3, 1
	s_add_u32 s4, s20, s3
	v_cndmask_b32_e64 v0, 0, 1, s[6:7]
	s_addc_u32 s5, s21, 0
	s_mov_b64 s[6:7], 0
	v_readfirstlane_b32 s61, v0

; __device__ __forceinline__ void phase_gemm(const Params& p, int kind, int j, unsigned char* lds) {
;     ...
;         } else if (kind == 2) {
;             tile_order(L, T / BM, 8, pm, pn);
;             td.A = (const bf16_t*)(big + B_YATT); td.Bt = wtb + WT_A_OUT / 2; td.ep.mode = 0; td.ep.out = big + B_OUTF_A2;
.LBB0_237:
	s_ashr_i32 s2, s60, 31
	s_lshr_b32 s2, s2, 29
	s_add_i32 s2, s60, s2
	s_and_b32 s3, s2, -8
	s_sub_i32 s3, s60, s3
	s_cmp_lt_i32 s3, 0
	s_movk_i32 s4, 0x61
	s_cselect_b32 s4, s4, 0x60
	s_mul_i32 s3, s4, s3
	s_ashr_i32 s2, s2, 3
	s_add_i32 s2, s3, s2
	s_ashr_i32 s3, s2, 31
	s_lshr_b32 s3, s3, 26
	s_add_i32 s3, s2, s3
	s_ashr_i32 s4, s3, 6
	s_lshl_b32 s4, s4, 3
	s_sub_i32 s5, 0x60, s4
	s_min_i32 s5, s5, 8
	v_cvt_f32_i32_e32 v0, s5
	s_andn2_b32 s3, s3, 63
	s_sub_i32 s6, s2, s3
	v_cvt_f32_i32_e32 v1, s6
	v_rcp_iflag_f32_e32 v2, v0
	s_xor_b32 s2, s6, s5
	s_ashr_i32 s2, s2, 30
	s_or_b32 s7, s2, 1
	v_mul_f32_e32 v2, v1, v2
	v_trunc_f32_e32 v2, v2
	v_fma_f32 v1, -v2, v0, v1
	v_cvt_i32_f32_e32 v2, v2
	v_cmp_ge_f32_e64 s[2:3], |v1|, |v0|
	s_and_b64 s[2:3], s[2:3], exec
	s_cselect_b32 s2, s7, 0
	v_readfirstlane_b32 s3, v2
	s_add_i32 s2, s3, s2
	s_sext_i32_i16 s64, s2
	s_mul_i32 s2, s2, s5
	s_sub_i32 s2, s6, s2
	s_sext_i32_i16 s2, s2
	s_add_i32 s2, s4, s2
	v_readlane_b32 s4, v253, 22
	v_readlane_b32 s6, v253, 42
	s_mov_b32 s61, 0
	s_mov_b64 s[68:69], 0x800
	s_mov_b64 s[12:13], 0
	s_movk_i32 s30, 0x800
	v_readlane_b32 s5, v253, 23
	v_readlane_b32 s7, v253, 43
	s_movk_i32 s3, 0x800
	s_mov_b64 s[94:95], 0
	s_mov_b64 s[90:91], s[20:21]

; #define WAIT_V(n) asm volatile("s_waitcnt vmcnt(" #n ")" ::: "memory")
; #define BAR __builtin_amdgcn_s_barrier()
; __device__ __forceinline__ void gemm_tile(const TileDesc& td, unsigned char* lds) {
;     ...
;     const int wid = tidk >> 6, lane = tidk & 63, wr = wid >> 2, wc = wid & 3, fr = lane & 15, fq = lane >> 4;
;     unsigned offA0, offA1, offB0, offB1;
;     { int _r, _c; stage_rc(tidk * 16, _r, _c); offA0 = (_r * lda + _c) * 2; offB0 = (((_r & ~31) | perm32(_r & 31)) * ldb + _c) * 2;
;       stage_rc(tidk * 16 + 8192, _r, _c); offA1 = (_r * lda + _c) * 2; offB1 = (((_r & ~31) | perm32(_r & 31)) * ldb + _c) * 2; }
;     f32x4 acc[2][2][4][2] = {};
;     bf16x8 At[4][2], B0[2][2], B1[2][2];
;     const int nt = __builtin_amdgcn_readfirstlane(td.K) / BK;
;     STAGE(SB(0, 0), Bt, ldb, bcol, 0); STAGE(SA(0, 0), A, lda, brow, 0);
;     STAGE(SB(0, 1), Bt, ldb, bcol + HALF, 0); STAGE(SA(0, 1), A, lda, brow + HALF, 0);
;     if (wr == 1) BAR;
;     WAIT_V(4); BAR;
;     STAGE(SB(1, 0), Bt, ldb, bcol, 1); STAGE(SA(1, 0), A, lda, brow, 1); STAGE(SB(1, 1), Bt, ldb, bcol + HALF, 1);
;     WAIT_V(6); BAR;
.LBB0_241:
	v_mov_b32_e32 v134, v158
	s_lshl_b32 s17, s2, 8
	v_bfe_i32 v2, v134, 27, 1
	v_lshlrev_b32_e32 v0, 4, v134
	v_lshrrev_b32_e32 v2, 22, v2
	v_add_u32_e32 v2, v0, v2
	v_and_b32_e32 v2, 0xfffffc00, v2
	v_sub_u32_e32 v2, v0, v2
	v_lshrrev_b32_e32 v3, 4, v2
	v_ashrrev_i32_e32 v1, 31, v134
	v_bitop3_b32 v2, v3, v2, 32 bitop3:0x6c
	v_lshrrev_b32_e32 v1, 26, v1
	v_ashrrev_i32_e32 v4, 31, v2
	v_add_u32_e32 v1, v134, v1
	v_lshrrev_b32_e32 v4, 26, v4
	v_ashrrev_i32_e32 v1, 6, v1
	v_add_u32_e32 v4, v2, v4
	v_lshlrev_b32_e32 v3, 3, v1
	v_ashrrev_i32_e32 v5, 6, v4
	v_and_b32_e32 v4, 0xc0, v4
	v_and_b32_e32 v3, -16, v3
	v_lshlrev_b32_e32 v1, 5, v1
	v_sub_u32_e32 v2, v2, v4
	v_add_u32_e32 v3, v5, v3
	v_and_b32_e32 v1, 32, v1
	v_ashrrev_i16_sdwa v2, v236, sext(v2) dst_sel:DWORD dst_unused:UNUSED_PAD src0_sel:DWORD src1_sel:BYTE_0
	v_add_u32_sdwa v1, v1, sext(v2) dst_sel:DWORD dst_unused:UNUSED_PAD src0_sel:DWORD src1_sel:WORD_0
	v_mul_lo_u32 v2, v3, s30
	v_add_lshl_u32 v128, v1, v2, 1
	v_lshlrev_b32_e32 v2, 1, v3
	v_lshrrev_b32_e32 v4, 2, v3
	v_and_b32_e32 v5, 3, v5
	s_movk_i32 s2, 0xffe0
	v_and_b32_e32 v2, 24, v2
	v_and_b32_e32 v4, 4, v4
	v_and_or_b32 v3, v3, s2, v5
	v_or3_b32 v2, v3, v4, v2
	v_mul_lo_u32 v2, v2, s3
	v_add_lshl_u32 v132, v2, v1, 1
	v_add_u32_e32 v1, 0x2000, v0
	v_ashrrev_i32_e32 v2, 31, v1
	v_lshrrev_b32_e32 v2, 22, v2
	v_add_u32_e32 v2, v1, v2
	v_ashrrev_i32_e32 v2, 10, v2
	v_mul_i32_i24_e32 v3, 0x400, v2
	v_sub_u32_e32 v1, v1, v3
	v_lshrrev_b32_e32 v3, 4, v1
	v_bitop3_b32 v1, v3, v1, 32 bitop3:0x6c
	v_ashrrev_i32_e32 v4, 31, v1
	v_lshrrev_b32_e32 v4, 26, v4
	v_add_u32_e32 v4, v1, v4
	v_lshlrev_b32_e32 v3, 3, v2
	v_ashrrev_i32_e32 v5, 6, v4
	v_and_b32_e32 v4, 0xc0, v4
	v_and_b32_e32 v3, -16, v3
	v_lshlrev_b32_e32 v2, 5, v2
	v_sub_u32_e32 v1, v1, v4
	v_add_u32_e32 v3, v5, v3
	v_and_b32_e32 v2, 32, v2
	v_ashrrev_i16_sdwa v1, v236, sext(v1) dst_sel:DWORD dst_unused:UNUSED_PAD src0_sel:DWORD src1_sel:BYTE_0
	s_lshl_b32 s16, s64, 8
	v_add_u32_sdwa v1, v2, sext(v1) dst_sel:DWORD dst_unused:UNUSED_PAD src0_sel:DWORD src1_sel:WORD_0
	v_mul_lo_u32 v2, v3, s30
	v_and_b32_e32 v5, 3, v5
	v_add_lshl_u32 v130, v1, v2, 1
	v_lshlrev_b32_e32 v2, 1, v3
	v_lshrrev_b32_e32 v4, 2, v3
	v_and_or_b32 v3, v3, s2, v5
	s_mul_hi_i32 s19, s16, s3
	s_mul_i32 s18, s16, s3
	v_readlane_b32 s2, v254, 2
	v_and_b32_e32 v2, 24, v2
	v_and_b32_e32 v4, 4, v4
	s_lshl_b64 s[18:19], s[18:19], 1
	v_add_u32_e32 v152, s2, v0
	v_or3_b32 v2, v3, v4, v2
	s_add_u32 s18, s6, s18
	v_readfirstlane_b32 s2, v152
	v_add_u32_e32 v153, 0x2000, v152
	s_mul_hi_i32 s25, s17, s30
	s_mul_i32 s24, s17, s30
	v_mul_lo_u32 v2, v2, s3
	s_addc_u32 s19, s7, s19
	s_mov_b32 m0, s2
	v_readfirstlane_b32 s2, v153
	s_lshl_b64 s[24:25], s[24:25], 1
	v_add_u32_e32 v139, 0, v0
	v_add_lshl_u32 v136, v2, v1, 1
	global_load_lds_dwordx4 v132, s[18:19]
	s_mov_b32 m0, s2
	s_add_u32 s24, s4, s24
	v_readfirstlane_b32 s2, v139
	v_add_u32_e32 v155, 0x2000, v139
	global_load_lds_dwordx4 v136, s[18:19]
	s_addc_u32 s25, s5, s25
	s_mov_b32 m0, s2
	v_readfirstlane_b32 s2, v155
	global_load_lds_dwordx4 v128, s[24:25]
	s_mov_b32 m0, s2
	s_or_b32 s2, s16, 0x80
	s_mul_hi_i32 s63, s2, s3
	s_mul_i32 s62, s2, s3
	v_readlane_b32 s2, v254, 3
	s_lshl_b64 s[62:63], s[62:63], 1
	s_add_u32 s80, s6, s62
	v_add_u32_e32 v156, s2, v0
	v_add_u32_e32 v157, 0x2000, v156
	v_readfirstlane_b32 s2, v156
	global_load_lds_dwordx4 v130, s[24:25]
	s_addc_u32 s81, s7, s63
	s_mov_b32 m0, s2
	v_readfirstlane_b32 s2, v157
	global_load_lds_dwordx4 v132, s[80:81]
	s_mov_b32 m0, s2
	s_or_b32 s2, s17, 0x80
	s_mul_hi_i32 s7, s2, s30
	s_mul_i32 s6, s2, s30
	s_lshl_b64 s[6:7], s[6:7], 1
	v_add_u32_e32 v174, 0x4000, v139
	s_add_u32 s4, s4, s6
	v_readfirstlane_b32 s2, v174
	v_add_u32_e32 v175, 0x6000, v139
	global_load_lds_dwordx4 v136, s[80:81]
	s_addc_u32 s5, s5, s7
	s_mov_b32 m0, s2
	v_readfirstlane_b32 s2, v175
	global_load_lds_dwordx4 v128, s[4:5]
	s_mov_b32 m0, s2
	v_ashrrev_i32_e32 v1, 8, v134
	global_load_lds_dwordx4 v130, s[4:5]
	v_cmp_eq_u32_e32 vcc, 1, v1
	s_and_saveexec_b64 s[6:7], vcc
	s_cbranch_execz .LBB0_243
	s_barrier
.LBB0_243:
	s_or_b64 exec, exec, s[6:7]
	v_readlane_b32 s2, v254, 4
	s_add_u32 s6, s18, 0x80
	s_addc_u32 s7, s19, 0
	v_add_u32_e32 v176, s2, v0
	v_mov_b32_e32 v137, v133
	v_readfirstlane_b32 s2, v176
	v_lshl_add_u64 v[2:3], s[6:7], 0, v[132:133]
	s_mov_b32 m0, s2
	v_add_u32_e32 v177, 0x2000, v176
	global_load_lds_dwordx4 v[2:3], off
	v_lshl_add_u64 v[2:3], s[6:7], 0, v[136:137]
	v_readfirstlane_b32 s2, v177
	s_add_u32 s6, s24, 0x80
	v_add_u32_e32 v178, 0x8000, v139
	v_mov_b32_e32 v129, v133
	s_mov_b32 m0, s2
	s_addc_u32 s7, s25, 0
	v_readfirstlane_b32 s2, v178
	v_add_u32_e32 v179, 0xa000, v139
	global_load_lds_dwordx4 v[2:3], off
	v_lshl_add_u64 v[2:3], s[6:7], 0, v[128:129]
	s_mov_b32 m0, s2
	v_readfirstlane_b32 s2, v179
	v_mov_b32_e32 v131, v133
	global_load_lds_dwordx4 v[2:3], off
	s_mov_b32 m0, s2
	v_readlane_b32 s2, v254, 5
	v_lshl_add_u64 v[2:3], s[6:7], 0, v[130:131]
	s_add_u32 s6, s80, 0x80
	v_add_u32_e32 v180, s2, v0
	s_addc_u32 s7, s81, 0
	v_readfirstlane_b32 s2, v180
	v_add_u32_e32 v181, 0x2000, v180
	global_load_lds_dwordx4 v[2:3], off
	v_lshl_add_u64 v[2:3], s[6:7], 0, v[132:133]
	s_mov_b32 m0, s2
	v_readfirstlane_b32 s2, v181
	global_load_lds_dwordx4 v[2:3], off
	v_lshl_add_u64 v[2:3], s[6:7], 0, v[136:137]
	s_mov_b32 m0, s2
	v_and_b32_e32 v0, 15, v134
	global_load_lds_dwordx4 v[2:3], off
	s_waitcnt vmcnt(10)
	s_barrier
	s_waitcnt vmcnt(6)
	v_lshlrev_b32_e32 v2, 6, v134
	v_lshlrev_b32_e32 v187, 6, v0
	v_lshlrev_b32_e32 v0, 2, v0
	v_and_b32_e32 v186, 48, v134
	s_cmpk_lg_i32 s30, 0x500
	v_and_b32_e32 v138, 0x3000, v2
	s_mov_b64 s[30:31], -1
	v_lshlrev_b32_e32 v154, 13, v1
	v_and_b32_e32 v188, 32, v0
	s_barrier
	s_cbranch_scc1 .LBB0_245
	v_lshlrev_b32_e32 v185, 13, v1
	v_or_b32_e32 v182, 0x400, v138
	v_or_b32_e32 v183, 0x800, v138
	v_or_b32_e32 v184, 0xc00, v138
	v_bitop3_b32 v142, v187, v188, v186 bitop3:0x36
	v_or_b32_e32 v144, 0x400, v185
	v_or_b32_e32 v145, 0x800, v185
	v_or_b32_e32 v146, 0xc00, v185
	v_or_b32_e32 v147, 0x1000, v185
	v_or_b32_e32 v148, 0x1400, v185
	v_or_b32_e32 v149, 0x1800, v185
	v_or_b32_e32 v150, 0x1c00, v185
	s_mov_b64 s[30:31], 0
; __device__ __forceinline__ void gemm_tile(const TileDesc& td, unsigned char* lds) {
;     ...
;     const int wid = tidk >> 6, lane = tidk & 63, wr = wid >> 2, wc = wid & 3, fr = lane & 15, fq = lane >> 4;
;     unsigned offA0, offA1, offB0, offB1;
;     { int _r, _c; stage_rc(tidk * 16, _r, _c); offA0 = (_r * lda + _c) * 2; offB0 = (((_r & ~31) | perm32(_r & 31)) * ldb + _c) * 2;
;       stage_rc(tidk * 16 + 8192, _r, _c); offA1 = (_r * lda + _c) * 2; offB1 = (((_r & ~31) | perm32(_r & 31)) * ldb + _c) * 2; }
;     f32x4 acc[2][2][4][2] = {};
;     bf16x8 At[4][2], B0[2][2], B1[2][2];
;     const int nt = __builtin_amdgcn_readfirstlane(td.K) / BK;
.LBB0_245:
	s_ashr_i32 s2, s3, 31
	s_lshr_b32 s2, s2, 26
	v_lshlrev_b32_e32 v0, 2, v134
	s_add_i32 s2, s3, s2
	v_and_b32_e32 v0, 32, v0
	s_ashr_i32 s6, s2, 6
	s_cmp_eq_u32 s30, 0
	s_cselect_b32 s6, 2, s6
	v_bitop3_b32 v0, v187, v0, v186 bitop3:0x36
	v_readlane_b32 s2, v254, 2
	v_mov_b32_e32 v103, 0
	s_andn2_b64 vcc, exec, s[30:31]
	v_add_u32_e32 v151, s2, v0
	v_readlane_b32 s2, v254, 3
	v_mov_b32_e32 v102, v103
	v_mov_b32_e32 v101, v103
	v_add_u32_e32 v143, s2, v0
	v_readlane_b32 s2, v254, 4
	v_mov_b32_e32 v100, v103
	v_mov_b32_e32 v127, v103
	v_add_u32_e32 v141, s2, v0
	v_readlane_b32 s2, v254, 5
	v_mov_b32_e32 v126, v103
	v_mov_b32_e32 v125, v103
	v_add_u32_e32 v140, s2, v0
	v_mov_b32_e32 v124, v103
	v_mov_b32_e32 v123, v103
	v_mov_b32_e32 v122, v103
	v_mov_b32_e32 v121, v103
	v_mov_b32_e32 v120, v103
	v_mov_b32_e32 v119, v103
	v_mov_b32_e32 v118, v103
	v_mov_b32_e32 v117, v103
	v_mov_b32_e32 v116, v103
	v_mov_b32_e32 v115, v103
	v_mov_b32_e32 v114, v103
	v_mov_b32_e32 v113, v103
	v_mov_b32_e32 v112, v103
	v_mov_b32_e32 v111, v103
	v_mov_b32_e32 v110, v103
	v_mov_b32_e32 v109, v103
	v_mov_b32_e32 v108, v103
	v_mov_b32_e32 v107, v103
	v_mov_b32_e32 v106, v103
	v_mov_b32_e32 v105, v103
	v_mov_b32_e32 v104, v103
	v_mov_b32_e32 v99, v103
	v_mov_b32_e32 v98, v103
	v_mov_b32_e32 v97, v103
	v_mov_b32_e32 v96, v103
	v_mov_b32_e32 v95, v103
	v_mov_b32_e32 v94, v103
	v_mov_b32_e32 v93, v103
	v_mov_b32_e32 v92, v103
	v_mov_b32_e32 v91, v103
	v_mov_b32_e32 v90, v103
	v_mov_b32_e32 v89, v103
	v_mov_b32_e32 v88, v103
	v_mov_b32_e32 v87, v103
	v_mov_b32_e32 v86, v103
	v_mov_b32_e32 v85, v103
	v_mov_b32_e32 v84, v103
	v_mov_b32_e32 v83, v103
	v_mov_b32_e32 v82, v103
	v_mov_b32_e32 v81, v103
	v_mov_b32_e32 v80, v103
	v_mov_b32_e32 v79, v103
	v_mov_b32_e32 v78, v103
	v_mov_b32_e32 v77, v103
	v_mov_b32_e32 v76, v103
	v_mov_b32_e32 v75, v103
	v_mov_b32_e32 v74, v103
	v_mov_b32_e32 v73, v103
	v_mov_b32_e32 v72, v103
	v_mov_b32_e32 v71, v103
	v_mov_b32_e32 v70, v103
	v_mov_b32_e32 v69, v103
	v_mov_b32_e32 v68, v103
	v_mov_b32_e32 v67, v103
	v_mov_b32_e32 v66, v103
	v_mov_b32_e32 v65, v103
	v_mov_b32_e32 v64, v103
	v_mov_b32_e32 v63, v103
	v_mov_b32_e32 v62, v103
	v_mov_b32_e32 v61, v103
	v_mov_b32_e32 v60, v103
	v_mov_b32_e32 v59, v103
	v_mov_b32_e32 v58, v103
	v_mov_b32_e32 v57, v103
	v_mov_b32_e32 v56, v103
	v_mov_b32_e32 v55, v103
	v_mov_b32_e32 v54, v103
	v_mov_b32_e32 v53, v103
	v_mov_b32_e32 v52, v103
	v_mov_b32_e32 v51, v103
	v_mov_b32_e32 v50, v103
	v_mov_b32_e32 v49, v103
	v_mov_b32_e32 v48, v103
	v_mov_b32_e32 v47, v103
	v_mov_b32_e32 v46, v103
	v_mov_b32_e32 v45, v103
	v_mov_b32_e32 v44, v103
	v_mov_b32_e32 v43, v103
	v_mov_b32_e32 v42, v103
	v_mov_b32_e32 v41, v103
	v_mov_b32_e32 v40, v103
	v_mov_b32_e32 v39, v103
	v_mov_b32_e32 v38, v103
	v_mov_b32_e32 v37, v103
	v_mov_b32_e32 v36, v103
	v_mov_b32_e32 v35, v103
	v_mov_b32_e32 v34, v103
	v_mov_b32_e32 v33, v103
	v_mov_b32_e32 v32, v103
	v_mov_b32_e32 v31, v103
	v_mov_b32_e32 v30, v103
	v_mov_b32_e32 v29, v103
	v_mov_b32_e32 v28, v103
	v_mov_b32_e32 v27, v103
	v_mov_b32_e32 v26, v103
	v_mov_b32_e32 v25, v103
	v_mov_b32_e32 v24, v103
	v_mov_b32_e32 v23, v103
	v_mov_b32_e32 v22, v103
	v_mov_b32_e32 v21, v103
	v_mov_b32_e32 v20, v103
	v_mov_b32_e32 v19, v103
	v_mov_b32_e32 v18, v103
	v_mov_b32_e32 v17, v103
	v_mov_b32_e32 v16, v103
	v_mov_b32_e32 v15, v103
	v_mov_b32_e32 v14, v103
	v_mov_b32_e32 v13, v103
	v_mov_b32_e32 v12, v103
	v_mov_b32_e32 v11, v103
	v_mov_b32_e32 v10, v103
	v_mov_b32_e32 v9, v103
	v_mov_b32_e32 v8, v103
	v_mov_b32_e32 v7, v103
	v_mov_b32_e32 v6, v103
	v_mov_b32_e32 v5, v103
	v_mov_b32_e32 v4, v103
	v_mov_b32_e32 v3, v103
	v_mov_b32_e32 v2, v103
	v_mov_b32_e32 v1, v103
	v_mov_b32_e32 v0, v103
	s_cbranch_vccnz .LBB0_249
; #define WAIT_V(n) asm volatile("s_waitcnt vmcnt(" #n ")" ::: "memory")
; #define BAR __builtin_amdgcn_s_barrier()
; __device__ __forceinline__ void gemm_tile(const TileDesc& td, unsigned char* lds) {
;     ...
;     f32x4 acc[2][2][4][2] = {};
;     bf16x8 At[4][2], B0[2][2], B1[2][2];
;     const int nt = __builtin_amdgcn_readfirstlane(td.K) / BK;
;     STAGE(SB(0, 0), Bt, ldb, bcol, 0); STAGE(SA(0, 0), A, lda, brow, 0);
;     STAGE(SB(0, 1), Bt, ldb, bcol + HALF, 0); STAGE(SA(0, 1), A, lda, brow + HALF, 0);
;     if (wr == 1) BAR;
;     WAIT_V(4); BAR;
;     STAGE(SB(1, 0), Bt, ldb, bcol, 1); STAGE(SA(1, 0), A, lda, brow, 1); STAGE(SB(1, 1), Bt, ldb, bcol + HALF, 1);
;     WAIT_V(6); BAR;
;     for (int t = 0; t < nt - 2; t += 2) {
	v_bitop3_b32 v142, v187, v188, v186 bitop3:0x36
	v_add_u32_e32 v182, 0, v142
	v_or_b32_e32 v145, 0x800, v154
	v_or_b32_e32 v147, 0x1000, v154
	v_or_b32_e32 v149, 0x1800, v154
	v_mov_b32_e32 v0, 0
	v_mov_b32_e32 v171, v135
	v_mov_b32_e32 v135, 0x2000
	v_mov_b32_e32 v167, 0x300000
	v_mov_b32_e32 v165, 0x358637bd
	v_mov_b32_e32 v250, 0x7fc00000
	v_mov_b32_e32 v173, 0x1000
	v_mov_b32_e32 v170, 0x3f1b4598
	v_mov_b32_e32 v172, 1
	v_mov_b32_e32 v251, 0x1fff
	v_mov_b32_e32 v159, 0xfff
	s_add_i32 s2, s6, -2
	v_or_b32_e32 v144, 0x400, v154
	v_or_b32_e32 v146, 0xc00, v154
	v_or_b32_e32 v148, 0x1400, v154
	v_or_b32_e32 v150, 0x1c00, v154
	s_mov_b32 s3, 0
	s_mov_b64 s[78:79], 0
	v_add_u32_e32 v183, v151, v138
	v_add_u32_e32 v184, v182, v145
	v_add_u32_e32 v185, v182, v147
	v_add_u32_e32 v186, v182, v149
	v_add_u32_e32 v187, v143, v138
	v_add_u32_e32 v188, v141, v138
	v_add_u32_e32 v189, v140, v138
	v_mov_b32_e32 v1, v0
	v_mov_b32_e32 v2, v0
	v_mov_b32_e32 v3, v0
	v_mov_b32_e32 v4, v0
	v_mov_b32_e32 v5, v0
	v_mov_b32_e32 v6, v0
	v_mov_b32_e32 v7, v0
	v_mov_b32_e32 v8, v0
	v_mov_b32_e32 v9, v0
	v_mov_b32_e32 v10, v0
	v_mov_b32_e32 v11, v0
	v_mov_b32_e32 v12, v0
	v_mov_b32_e32 v13, v0
	v_mov_b32_e32 v14, v0
	v_mov_b32_e32 v15, v0
	v_mov_b32_e32 v16, v0
	v_mov_b32_e32 v17, v0
	v_mov_b32_e32 v18, v0
	v_mov_b32_e32 v19, v0
	v_mov_b32_e32 v20, v0
	v_mov_b32_e32 v21, v0
	v_mov_b32_e32 v22, v0
	v_mov_b32_e32 v23, v0
	v_mov_b32_e32 v24, v0
	v_mov_b32_e32 v25, v0
	v_mov_b32_e32 v26, v0
	v_mov_b32_e32 v27, v0
	v_mov_b32_e32 v28, v0
	v_mov_b32_e32 v29, v0
	v_mov_b32_e32 v30, v0
	v_mov_b32_e32 v31, v0
	v_mov_b32_e32 v32, v0
	v_mov_b32_e32 v33, v0
	v_mov_b32_e32 v34, v0
	v_mov_b32_e32 v35, v0
	v_mov_b32_e32 v36, v0
	v_mov_b32_e32 v37, v0
	v_mov_b32_e32 v38, v0
	v_mov_b32_e32 v39, v0
	v_mov_b32_e32 v40, v0
	v_mov_b32_e32 v41, v0
	v_mov_b32_e32 v42, v0
	v_mov_b32_e32 v43, v0
	v_mov_b32_e32 v44, v0
	v_mov_b32_e32 v45, v0
	v_mov_b32_e32 v46, v0
	v_mov_b32_e32 v47, v0
	v_mov_b32_e32 v48, v0
	v_mov_b32_e32 v49, v0
	v_mov_b32_e32 v50, v0
	v_mov_b32_e32 v51, v0
	v_mov_b32_e32 v52, v0
	v_mov_b32_e32 v53, v0
	v_mov_b32_e32 v54, v0
	v_mov_b32_e32 v55, v0
	v_mov_b32_e32 v56, v0
	v_mov_b32_e32 v57, v0
	v_mov_b32_e32 v58, v0
	v_mov_b32_e32 v59, v0
	v_mov_b32_e32 v60, v0
	v_mov_b32_e32 v61, v0
	v_mov_b32_e32 v62, v0
	v_mov_b32_e32 v63, v0
	v_mov_b32_e32 v64, v0
	v_mov_b32_e32 v65, v0
	v_mov_b32_e32 v66, v0
	v_mov_b32_e32 v67, v0
	v_mov_b32_e32 v68, v0
	v_mov_b32_e32 v69, v0
	v_mov_b32_e32 v70, v0
	v_mov_b32_e32 v71, v0
	v_mov_b32_e32 v72, v0
	v_mov_b32_e32 v73, v0
	v_mov_b32_e32 v74, v0
	v_mov_b32_e32 v75, v0
	v_mov_b32_e32 v76, v0
	v_mov_b32_e32 v77, v0
	v_mov_b32_e32 v78, v0
	v_mov_b32_e32 v79, v0
	v_mov_b32_e32 v80, v0
	v_mov_b32_e32 v81, v0
	v_mov_b32_e32 v82, v0
	v_mov_b32_e32 v83, v0
	v_mov_b32_e32 v84, v0
	v_mov_b32_e32 v85, v0
	v_mov_b32_e32 v86, v0
	v_mov_b32_e32 v87, v0
	v_mov_b32_e32 v88, v0
	v_mov_b32_e32 v89, v0
	v_mov_b32_e32 v90, v0
	v_mov_b32_e32 v91, v0
	v_mov_b32_e32 v92, v0
	v_mov_b32_e32 v93, v0
	v_mov_b32_e32 v94, v0
	v_mov_b32_e32 v95, v0
	v_mov_b32_e32 v96, v0
	v_mov_b32_e32 v97, v0
	v_mov_b32_e32 v98, v0
	v_mov_b32_e32 v99, v0
	v_mov_b32_e32 v104, v0
	v_mov_b32_e32 v105, v0
	v_mov_b32_e32 v106, v0
	v_mov_b32_e32 v107, v0
	v_mov_b32_e32 v108, v0
	v_mov_b32_e32 v109, v0
	v_mov_b32_e32 v110, v0
	v_mov_b32_e32 v111, v0
	v_mov_b32_e32 v112, v0
	v_mov_b32_e32 v113, v0
	v_mov_b32_e32 v114, v0
	v_mov_b32_e32 v115, v0
	v_mov_b32_e32 v116, v0
	v_mov_b32_e32 v117, v0
	v_mov_b32_e32 v118, v0
	v_mov_b32_e32 v119, v0
	v_mov_b32_e32 v120, v0
	v_mov_b32_e32 v121, v0
	v_mov_b32_e32 v122, v0
	v_mov_b32_e32 v123, v0
	v_mov_b32_e32 v124, v0
	v_mov_b32_e32 v125, v0
	v_mov_b32_e32 v126, v0
	v_mov_b32_e32 v127, v0
	v_mov_b32_e32 v100, v0
	v_mov_b32_e32 v101, v0
	v_mov_b32_e32 v102, v0
	v_mov_b32_e32 v103, v0
